# phase15 fast path: DMA issue of tile i+3 moved from the iteration tail to behind the QK MFMAs
# speedup vs baseline: 1.0109x; 1.0109x over previous
; #define NSA_FETCH(rk, rv, e) do { const int v_ = lst[(e)]; \
;       const u16* kp_ = (v_ < 64) ? ksb + (size_t)v_ * 64 * 128 : kwb + (size_t)(v_ - 64) * 64 * 128; \
;       const u16* vp_ = (v_ < 64) ? vsb + v_ * 64 : vwb + (v_ - 64) * 64; \
;       rk = *(const uint4*)(kp_ + (size_t)pr * 128 + pc * 8); rv = *(const uint4*)(vp_ + (size_t)pr * SEQ + pc * 8); } while (0)
; #define NSA_PUT(rk, rv, buf) do { *(uint4*)(sK + (buf) * 2 * 64 * LDSP + prl * LDSP + pc * 8) = rk; \
;       *(uint4*)(sV + (buf) * 2 * 64 * LDSP + pr * LDSP + pc * 8) = rv; } while (0)
; __device__ __forceinline__ void phase_nsa_sw(const Params& p, u16* sm) {
;     ...
;     NSA_FETCH(rkA, rvA, 0);
;     NSA_PUT(rkA, rvA, 0);
;     if (ntl > 1) NSA_FETCH(rkA, rvA, 1);
;     nsa_reset(st);
;     for (int i = 0; i < ntl; ++i) {
;       __syncthreads();
;       const int v = lst[i];
;       const u16* cK = sK + (i & 1) * 2 * 64 * LDSP;
;       const u16* cV = sV + (i & 1) * 2 * 64 * LDSP;
;       if (i == nsel) {
;     ...
;       if (i + 1 < ntl) NSA_PUT(rkA, rvA, (i + 1) & 1);
;       if (i + 2 < ntl) NSA_FETCH(rkA, rvA, i + 2);
;     }
.Lfp15_tail:
	s_add_i32 s10, s42, 1
	v_cmp_ge_i32_e64 s[8:9], s10, v231
	s_add_i32 s83, s83, 4
	s_addk_i32 s89, 0x80
	s_and_b64 vcc, exec, s[8:9]
	s_cbranch_vccnz .LBB0_1323
	s_mov_b32 s42, s10
	v_readfirstlane_b32 s11, v192
	s_nop 3
	s_cmp_lt_u32 s11, 0x100
	s_cbranch_scc1 .LBB0_1336
	v_readlane_b32 s14, v24, s42
	v_readlane_b32 s15, v25, s42
	v_cmp_ne_u32_e32 vcc, s42, v203
	s_cmp_lt_u32 s42, 64
	s_cselect_b32 s14, s14, s15
	s_cbranch_vccz .Lfp15_park
	s_branch .Lfp15_dispatch

; __device__ __forceinline__ void nsa_qk(f32x4 (&s)[2][4], const u16* sK, const bf16x8 (&qf)[2][2], int fr, int fq) {
; #pragma unroll
;   for (int mt = 0; mt < 4; ++mt) {
;     s[0][mt] = (f32x4){0.f, 0.f, 0.f, 0.f}; s[1][mt] = (f32x4){0.f, 0.f, 0.f, 0.f};
; #pragma unroll
;     for (int ks = 0; ks < 2; ++ks) {
;       bf16x8 kf = *(const bf16x8*)(sK + (mt * 16 + fr) * LDSP + ks * 32 + fq * 8);
;       s[0][mt] = mfma16(kf, qf[0][ks], s[0][mt]);
;       s[1][mt] = mfma16(kf, qf[1][ks], s[1][mt]);
;     }
;   }
; }
; template <bool MASKED>
; __device__ __forceinline__ void nsa_online_step(NsaState& st, f32x4 (&s)[2][4], unsigned vmask, bool lanevalid, const u16* sV, int fr, int fq) {
;     ...
; #pragma unroll
;       for (int mt = 0; mt < 4; ++mt)
; #pragma unroll
;         for (int j = 0; j < 4; ++j) tmax = fmaxf(tmax, s[hh][mt][j]);
;       tmax = lanevalid ? tmax : -1e30f;
;     }
;     tmax = fmaxf(tmax, __shfl_xor(tmax, 16));
;     tmax = fmaxf(tmax, __shfl_xor(tmax, 32));
;     const bool upd = tmax > st.m[hh] + DEFER;
;     if (__ballot(upd) != 0ull) {
;       const float mnew = upd ? tmax : st.m[hh];
;       const float alpha = __builtin_amdgcn_exp2f((st.m[hh] - mnew) * SM_C);
;       st.m[hh] = mnew;
; #pragma unroll
;       for (int dm = 0; dm < 4; ++dm) st.acc[hh][dm] *= alpha;
;       st.accL[hh] *= alpha;
;     }
;     const float nb = -st.m[hh] * SM_C;
; #pragma unroll
;     for (int k2 = 0; k2 < 2; ++k2) {
;       uint32_t pw[4];
; #pragma unroll
;       for (int e2 = 0; e2 < 4; ++e2) {
;         const int mt = 2 * k2 + (e2 >> 1), j = (e2 & 1) * 2;
;         float p0 = __builtin_amdgcn_exp2f(__builtin_fmaf(s[hh][mt][j], SM_C, nb));
;         float p1 = __builtin_amdgcn_exp2f(__builtin_fmaf(s[hh][mt][j + 1], SM_C, nb));
;         if (MASKED) {
;           p0 = ((vmask >> (mt * 4 + j)) & 1u) ? p0 : 0.f;
;           p1 = ((vmask >> (mt * 4 + j + 1)) & 1u) ? p1 : 0.f;
;         }
;         pw[e2] = pack2(p0, p1);
.Lfp15_lvdone:
	s_mov_b32 s20, 0x3e38aa3b
	s_waitcnt lgkmcnt(4)
	v_mfma_f32_16x16x32_bf16 v[68:71], v[136:139], v[4:7], 0
	v_mfma_f32_16x16x32_bf16 v[72:75], v[144:147], v[4:7], 0
	v_mfma_f32_16x16x32_bf16 v[68:71], v[140:143], v[8:11], v[68:71]
	v_mfma_f32_16x16x32_bf16 v[72:75], v[148:151], v[8:11], v[72:75]
	s_waitcnt lgkmcnt(0)
	ds_read_b128 v[28:31], v2 offset:9216
	ds_read_b128 v[36:39], v2 offset:11520
	ds_read_b128 v[44:47], v2 offset:13824
	ds_read_b128 v[124:127], v2 offset:16128
	ds_read_b128 v[32:35], v2 offset:9280
	ds_read_b128 v[40:43], v2 offset:11584
	ds_read_b128 v[120:123], v2 offset:13888
	ds_read_b128 v[128:131], v2 offset:16192
	v_mfma_f32_16x16x32_bf16 v[76:79], v[152:155], v[4:7], 0
	v_mfma_f32_16x16x32_bf16 v[80:83], v[160:163], v[4:7], 0
	v_mfma_f32_16x16x32_bf16 v[76:79], v[156:159], v[8:11], v[76:79]
	v_mfma_f32_16x16x32_bf16 v[80:83], v[164:167], v[8:11], v[80:83]
	v_mfma_f32_16x16x32_bf16 v[84:87], v[136:139], v[12:15], 0
	v_mfma_f32_16x16x32_bf16 v[88:91], v[144:147], v[12:15], 0
	v_mfma_f32_16x16x32_bf16 v[84:87], v[140:143], v[16:19], v[84:87]
	v_mfma_f32_16x16x32_bf16 v[88:91], v[148:151], v[16:19], v[88:91]
	v_mfma_f32_16x16x32_bf16 v[92:95], v[152:155], v[12:15], 0
	v_mfma_f32_16x16x32_bf16 v[96:99], v[160:163], v[12:15], 0
	v_mfma_f32_16x16x32_bf16 v[92:95], v[156:159], v[16:19], v[92:95]
	v_mfma_f32_16x16x32_bf16 v[96:99], v[164:167], v[16:19], v[96:99]
	v_readfirstlane_b32 s13, v231
	s_add_i32 s11, s42, 3
	s_and_b32 s12, s11, 1
	s_mulk_i32 s12, 0x4800
	s_and_b32 s18, s11, 2
	s_mul_i32 s18, s18, 0x9000
	s_add_i32 s12, s12, s18
	s_add_i32 s13, s13, -1
	s_min_i32 s11, s11, s13
	v_readlane_b32 s18, v24, s11
	v_readlane_b32 s19, v25, s11
	s_cmp_lt_u32 s11, 64
	s_cselect_b32 s11, s18, s19
	s_cmp_lt_i32 s11, 64
	s_cselect_b32 s14, s62, s78
	s_cselect_b32 s15, s63, s79
	s_cselect_b32 s16, s66, s80
	s_cselect_b32 s17, s67, s81
	s_and_b32 s13, s11, 63
	s_lshl_b32 s18, s13, 14
	s_lshl_b32 s13, s13, 7
	s_add_u32 s14, s14, s18
	s_addc_u32 s15, s15, 0
	s_add_u32 s16, s16, s13
	s_addc_u32 s17, s17, 0
	v_readfirstlane_b32 s18, v251
	v_readfirstlane_b32 s19, v252
	s_nop 0
	s_add_u32 s18, s18, s12
	s_mov_b32 m0, s18
	s_add_u32 s18, s18, 0x2400
	global_load_lds_dwordx4 v248, s[14:15]
	s_mov_b32 m0, s18
	s_cmp_ge_u32 s19, 0x2400
	global_load_lds_dwordx4 v249, s[16:17]
	s_cselect_b32 s14, s16, s14
	s_cselect_b32 s15, s17, s15
	s_add_u32 s19, s19, s12
	s_mov_b32 m0, s19
	s_mov_b64 exec, 0xffff
	global_load_lds_dwordx4 v250, s[14:15]
	s_mov_b64 exec, -1
	v_max3_f32 v1, v68, v69, v70
	v_max3_f32 v1, v1, v71, v72
	v_max3_f32 v1, v1, v73, v74
	v_max3_f32 v1, v1, v75, v76
	v_max3_f32 v1, v1, v77, v78
	v_max3_f32 v1, v1, v79, v80
	v_max3_f32 v1, v1, v81, v82
	v_max_f32_e32 v1, v1, v83
	v_add_f32_e32 v168, 0x42317218, v234
	v_cmp_gt_f32_e32 vcc, v1, v168
	s_and_b64 s[8:9], vcc, s[30:31]
	s_cbranch_scc1 .Lfp15_upd0
.Lfp15_noupd0:
	v_mul_f32_e32 v2, 0xbe38aa3b, v234
	v_cndmask_b32_e64 v2, v221, v2, s[30:31]
	v_pk_fma_f32 v[136:137], v[68:69], s[20:21], v[2:3] op_sel_hi:[1,0,0]
	v_pk_fma_f32 v[138:139], v[70:71], s[20:21], v[2:3] op_sel_hi:[1,0,0]
	v_exp_f32_e32 v136, v136
	v_exp_f32_e32 v137, v137
	v_exp_f32_e32 v138, v138
	v_exp_f32_e32 v139, v139
	v_pk_fma_f32 v[140:141], v[72:73], s[20:21], v[2:3] op_sel_hi:[1,0,0]
	v_pk_fma_f32 v[142:143], v[74:75], s[20:21], v[2:3] op_sel_hi:[1,0,0]
	v_cvt_pk_bf16_f32 v236, v136, v137
	v_cvt_pk_bf16_f32 v237, v138, v139
	v_exp_f32_e32 v140, v140
	v_exp_f32_e32 v141, v141
	v_exp_f32_e32 v142, v142
	v_exp_f32_e32 v143, v143
	v_pk_fma_f32 v[144:145], v[76:77], s[20:21], v[2:3] op_sel_hi:[1,0,0]
	v_pk_fma_f32 v[146:147], v[78:79], s[20:21], v[2:3] op_sel_hi:[1,0,0]
	v_cvt_pk_bf16_f32 v238, v140, v141
	v_cvt_pk_bf16_f32 v239, v142, v143
	v_exp_f32_e32 v144, v144
	v_exp_f32_e32 v145, v145
	v_exp_f32_e32 v146, v146
	v_exp_f32_e32 v147, v147
	v_pk_fma_f32 v[148:149], v[80:81], s[20:21], v[2:3] op_sel_hi:[1,0,0]
	v_pk_fma_f32 v[150:151], v[82:83], s[20:21], v[2:3] op_sel_hi:[1,0,0]
	v_cvt_pk_bf16_f32 v240, v144, v145
	v_cvt_pk_bf16_f32 v241, v146, v147
	v_exp_f32_e32 v148, v148
	v_exp_f32_e32 v149, v149
	v_exp_f32_e32 v150, v150
	v_exp_f32_e32 v151, v151
.Lfp15_xend:
	v_readfirstlane_b32 s8, v192
	v_cvt_pk_bf16_f32 v242, v148, v149
	v_cvt_pk_bf16_f32 v243, v150, v151
	s_cmp_lt_u32 s8, 0x100
	s_cbranch_scc1 .Lfp15_ystart
	s_waitcnt vmcnt(6)
	s_waitcnt lgkmcnt(0)
	s_barrier

; template <bool MASKED>
; __device__ __forceinline__ void nsa_online_step(NsaState& st, f32x4 (&s)[2][4], unsigned vmask, bool lanevalid, const u16* sV, int fr, int fq) {
;     ...
;     const float nb = -st.m[hh] * SM_C;
; #pragma unroll
;     for (int k2 = 0; k2 < 2; ++k2) {
;       uint32_t pw[4];
; #pragma unroll
;       for (int e2 = 0; e2 < 4; ++e2) {
;         const int mt = 2 * k2 + (e2 >> 1), j = (e2 & 1) * 2;
;         float p0 = __builtin_amdgcn_exp2f(__builtin_fmaf(s[hh][mt][j], SM_C, nb));
;         float p1 = __builtin_amdgcn_exp2f(__builtin_fmaf(s[hh][mt][j + 1], SM_C, nb));
;         if (MASKED) {
;           p0 = ((vmask >> (mt * 4 + j)) & 1u) ? p0 : 0.f;
;           p1 = ((vmask >> (mt * 4 + j + 1)) & 1u) ? p1 : 0.f;
;         }
;         pw[e2] = pack2(p0, p1);
;         if (!MASKED) pw[e2] &= lmask;
;       }
;       pf[hh][k2] = mk_frag(pw[0], pw[1], pw[2], pw[3]);
;       st.accL[hh] = mfma16(ones, pf[hh][k2], st.accL[hh]);
;     }
; #pragma unroll
;     for (int k2 = 0; k2 < 2; ++k2)
; #pragma unroll
;       for (int dm = 0; dm < 4; ++dm) {
;         const bf16x8 vf = *(const bf16x8*)(sV + (dm * 16 + fr) * LDSP + k2 * 32 + fq * 8);
;         st.acc[hh][dm] = mfma16(vf, pf[hh][k2], st.acc[hh][dm]);
;       }
.Lfp15_noupd1:
	v_mul_f32_e32 v2, 0xbe38aa3b, v235
	v_cndmask_b32_e64 v2, v221, v2, s[30:31]
	v_pk_fma_f32 v[136:137], v[84:85], s[20:21], v[2:3] op_sel_hi:[1,0,0]
	v_pk_fma_f32 v[138:139], v[86:87], s[20:21], v[2:3] op_sel_hi:[1,0,0]
	v_exp_f32_e32 v136, v136
	v_exp_f32_e32 v137, v137
	v_exp_f32_e32 v138, v138
	v_mfma_f32_16x16x32_bf16 v[48:51], v[20:23], v[240:243], v[48:51]
	v_exp_f32_e32 v139, v139
	v_pk_fma_f32 v[140:141], v[88:89], s[20:21], v[2:3] op_sel_hi:[1,0,0]
	v_pk_fma_f32 v[142:143], v[90:91], s[20:21], v[2:3] op_sel_hi:[1,0,0]
	v_cvt_pk_bf16_f32 v244, v136, v137
	v_cvt_pk_bf16_f32 v245, v138, v139
	v_mfma_f32_16x16x32_bf16 v[52:55], v[32:35], v[240:243], v[52:55]
	v_exp_f32_e32 v140, v140
	v_exp_f32_e32 v141, v141
	v_exp_f32_e32 v142, v142
	v_exp_f32_e32 v143, v143
	v_pk_fma_f32 v[144:145], v[92:93], s[20:21], v[2:3] op_sel_hi:[1,0,0]
	v_mfma_f32_16x16x32_bf16 v[56:59], v[40:43], v[240:243], v[56:59]
	v_pk_fma_f32 v[146:147], v[94:95], s[20:21], v[2:3] op_sel_hi:[1,0,0]
	v_cvt_pk_bf16_f32 v246, v140, v141
	v_cvt_pk_bf16_f32 v247, v142, v143
	v_exp_f32_e32 v144, v144
	v_exp_f32_e32 v145, v145
	v_mfma_f32_16x16x32_bf16 v[60:63], v[120:123], v[240:243], v[60:63]
	v_exp_f32_e32 v146, v146
	v_exp_f32_e32 v147, v147
	v_pk_fma_f32 v[148:149], v[96:97], s[20:21], v[2:3] op_sel_hi:[1,0,0]
	v_pk_fma_f32 v[150:151], v[98:99], s[20:21], v[2:3] op_sel_hi:[1,0,0]
	v_cvt_pk_bf16_f32 v100, v144, v145
	v_mfma_f32_16x16x32_bf16 v[64:67], v[128:131], v[240:243], v[64:67]
	v_cvt_pk_bf16_f32 v101, v146, v147
	v_exp_f32_e32 v148, v148
	v_exp_f32_e32 v149, v149
	v_exp_f32_e32 v150, v150
	v_exp_f32_e32 v151, v151
	s_nop 0
	v_cvt_pk_bf16_f32 v102, v148, v149
	v_cvt_pk_bf16_f32 v103, v150, v151
	s_nop 0
	v_mfma_f32_16x16x32_bf16 v[132:135], v[20:23], v[244:247], v[132:135]
	v_mfma_f32_16x16x32_bf16 v[116:119], v[28:31], v[244:247], v[116:119]
	v_mfma_f32_16x16x32_bf16 v[112:115], v[36:39], v[244:247], v[112:115]
	v_mfma_f32_16x16x32_bf16 v[108:111], v[44:47], v[244:247], v[108:111]
	v_mfma_f32_16x16x32_bf16 v[104:107], v[124:127], v[244:247], v[104:107]
	v_mfma_f32_16x16x32_bf16 v[132:135], v[20:23], v[100:103], v[132:135]
	v_mfma_f32_16x16x32_bf16 v[116:119], v[32:35], v[100:103], v[116:119]
	v_mfma_f32_16x16x32_bf16 v[112:115], v[40:43], v[100:103], v[112:115]
	v_mfma_f32_16x16x32_bf16 v[108:111], v[120:123], v[100:103], v[108:111]
	v_mfma_f32_16x16x32_bf16 v[104:107], v[128:131], v[100:103], v[104:107]
	s_branch .Lfp15_tail
